# retention-output units moved from a static pre-pass into the attention work queue (slots 256..511) so their load chains overlap other workgroups' attention items
# baseline (speedup 1.0000x reference)
; #define LAS __attribute__((address_space(3)))
; __device__ __forceinline__ float ret_log2g(int hr) { return log2f(1.0f - exp2f(-(5.0f + (float)hr))); }
; #define REP(k) for (int rep_ = (spin_t0 = (((PROBE_SPIN_MASK >> (k)) & 1u) ? __builtin_amdgcn_s_memrealtime() : 0ull), 0); rep_ < (((PROBE_MASK >> (k)) & 1u) ? 1 + PROBE_REP : 1); ++rep_, spin_acc += (((PROBE_SPIN_MASK >> (k)) & 1u) ? __builtin_amdgcn_s_memrealtime() - spin_t0 : 0ull))
; __device__ __forceinline__ void retout_phase(const bf16_t* RQ, const bf16_t* RK, const bf16_t* RV, const bf16_t* RG, const bf16_t* ST, bf16_t* Y, lptr lds, int blk, int G, int tid_) {
;     for (int unit = blk; unit < 256; unit += G) {
;         int tid = tid_; asm volatile("" : "+v"(tid));
;         const int wid = __builtin_amdgcn_readfirstlane(tid >> 6), lane = tid & 63, r32 = lane & 31, hi = lane >> 5;
;         const int ci = wid >> 1, tb = wid & 1, bhr = unit >> 4, n = (unit & 15) * 4 + ci, hr = bhr & 3, b = bhr >> 2;
;         const float l2g = ret_log2g(hr);
;         const size_t rowbase = (size_t)bhr * SEQ + n * 64;
; template <unsigned PHMASK> __global__ void __launch_bounds__(NTHREADS, 2) fwd(Args a) {
;     ...
;         if (IN(6)) REP(6) {
;             { PH_ENTER();
;               bf16_t *RQ = (bf16_t*)(ws + WS_RQ), *RK = (bf16_t*)(ws + WS_RK), *RV = (bf16_t*)(ws + WS_RV), *RG = (bf16_t*)(ws + WS_RG), *Y = (bf16_t*)(ws + WS_Y);
;               float* rsp = (float*)(ws + WS_RSP);
;               if (NAIVE_MASK & 2) { for (int un = blk; un < 16 * 64; un += G) { const int bhr = un >> 6, n = un & 63, b = bhr >> 2, hr = bhr & 3; const size_t ro = ((size_t)bhr * SEQ + n * 64) * HD;
;                   retout_unit(RQ + ro, RK + ro, RV + ro, RG + ro, rsp + (size_t)un * 128 * 128, Y + ((size_t)(b * SEQ + n * 64)) * DM + 1024 + hr * 128, ret_log2g(hr), (LAS float*)lds, tid); } }
;               else mx::retout_phase(RQ, RK, RV, RG, (const bf16_t*)rsp, Y, (mx::lptr)lds, blk, G, tid); }
;             { PH_ENTER(); int l = l0; LS(l);
;               fa::attn_phase((const bf16_t*)(ws + WS_FQ), (const bf16_t*)(ws + WS_FK), (const bf16_t*)(ws + WS_FV), (const float*)(ws + WS_CUM), (const float*)(ws + WS_NORM), (bf16_t*)(ws + WS_Y),
;                              (unsigned*)(ws + WS_CTL) + CW_QUEUE + 64 * (2 * l + (rep_ & 1)), (unsigned*)(ws + WS_CTL) + CW_FLAGS + (size_t)l * 1024, (float*)(ws + WS_PART), (fa::lptr)lds, tid); }
.LBB0_774:
	v_readlane_b32 s0, v254, 34
	v_readlane_b32 s1, v254, 35
	s_andn2_b64 vcc, exec, s[0:1]
	s_cbranch_vccnz .LBB0_1004
	s_waitcnt lgkmcnt(0)
	v_mov_b32_e32 v1, v0
	v_readlane_b32 s14, v254, 0
	v_readlane_b32 s15, v254, 3
	s_mov_b64 s[0:1], 0
	s_cmpk_gt_i32 s14, 0xff
	s_branch .LBB0_820
.Lret_item:
	v_mov_b32_e32 v1, v0
	s_mov_b32 s14, s6
	s_mov_b64 s[0:1], 0
	s_movk_i32 s85, 0x2000
	s_mov_b32 s61, 0x42fc0000
	v_readlane_b32 s4, v254, 56
	v_readlane_b32 s5, v254, 57
	s_load_dwordx2 s[4:5], s[4:5], 0xa0
	s_waitcnt lgkmcnt(0)
	s_add_u32 s16, s4, s0
	s_addc_u32 s17, s5, s1
	s_add_u32 s0, s16, 0x33800000
	s_addc_u32 s1, s17, 0
	s_add_u32 s6, s16, 0x34800000
	s_addc_u32 s7, s17, 0
	s_add_u32 s8, s16, 0x35800000
	s_addc_u32 s9, s17, 0
	s_add_u32 s10, s16, 0x36800000
	s_addc_u32 s11, s17, 0
	s_add_u32 s18, s16, 0x41800000
	s_addc_u32 s19, s17, 0
	s_lshl_b32 s20, s14, 6
	s_lshl_b32 s21, s15, 6
	s_lshl_b32 s22, s14, 2
	s_lshl_b32 s23, s15, 2
	s_branch .LBB0_778
.LBB0_777:
	s_or_b64 exec, exec, s[4:5]
	s_branch .LBB0_820

; __device__ __forceinline__ void item_decode(int item, int& qb, int& bh, int& nh, int& half) {
;     constexpr int GQ[16] = {13, 12, 11, 10, 9, 8, 15, 7, 14, 6, 5, 4, 3, 2, 1, 0};
;     int base = 0; qb = 0; nh = 1; half = 0; bh = 0;
; #pragma unroll
;     for (int g = 0; g < 16; ++g) { const int q = GQ[g], n = q >= 14 ? 2 : 1, cnt = 32 * n; if (item >= base && item < base + cnt) { const int r = item - base; qb = q; nh = n; bh = r % 32; half = n == 2 ? 1 - r / 32 : 0; } base += cnt; }
; }
; __device__ __forceinline__ void attn_phase(const bf16_t* FQ, const bf16_t* FK, const bf16_t* FV, const float* cum, const float* norms, bf16_t* Y, unsigned* qctr, unsigned* flags, float* parts, lptr lds, int tid_) {
;     ...
;     for (;;) {
;         int tid = tid_; asm volatile("" : "+v"(tid));
;         const int wid = __builtin_amdgcn_readfirstlane(tid >> 6), lane = tid & 63;
;         __syncthreads();
;         if (tid == 0) sh[0] = (int)__hip_atomic_fetch_add(qctr, 1u, __ATOMIC_RELAXED, __HIP_MEMORY_SCOPE_AGENT);
;         __syncthreads();
;         const int item = sh[0];
;         if (item >= N_ITEMS) break;
;         int qb, bh, nh, half; item_decode(item, qb, bh, nh, half);
.LBB0_828:
	s_or_b64 exec, exec, s[0:1]
	v_mov_b32_e32 v1, s62
	s_waitcnt lgkmcnt(0)
	s_barrier
	ds_read_b32 v1, v1
	s_movk_i32 s0, 0x23f
	s_waitcnt lgkmcnt(0)
	v_cmp_lt_i32_e32 vcc, s0, v1
	v_readfirstlane_b32 s6, v1
	s_mov_b64 s[0:1], -1
	s_nop 0
	s_cmp_gt_u32 s6, 0x33f
	s_cbranch_scc1 .LBB0_823
	s_cmp_lt_u32 s6, 0x100
	s_cbranch_scc1 .Lattn_item
	s_sub_i32 s6, s6, 0x100
	s_cmp_lt_u32 s6, 0x100
	s_cbranch_scc1 .Lret_item
.Lattn_item:
	s_and_b32 s0, s6, 31
	s_cmp_lt_u32 s6, 32
	s_cselect_b64 s[8:9], -1, 0
	s_and_b64 s[14:15], s[8:9], exec
	s_cselect_b32 s7, 13, 0
	s_and_b32 s1, s6, 0xffffffe0
	s_cmp_eq_u32 s1, 32
	s_cselect_b64 s[14:15], -1, 0
	s_and_b64 s[16:17], s[14:15], exec
	s_cselect_b32 s7, 12, s7
	s_cmp_eq_u32 s1, 64
	s_cselect_b64 s[16:17], -1, 0
	s_and_b64 s[18:19], s[16:17], exec
	s_cselect_b32 s7, 11, s7
	s_or_b64 s[14:15], s[14:15], s[16:17]
	s_or_b64 s[8:9], s[14:15], s[8:9]
	s_cmpk_eq_i32 s1, 0x60
	s_cselect_b64 s[14:15], -1, 0
	s_and_b64 s[16:17], s[14:15], exec
	s_cselect_b32 s7, 10, s7
	s_or_b64 s[8:9], s[14:15], s[8:9]
	s_cmpk_eq_i32 s1, 0x80
	s_cselect_b64 s[14:15], -1, 0
	s_and_b64 s[16:17], s[14:15], exec
	s_cselect_b32 s7, 9, s7
	s_or_b64 s[8:9], s[14:15], s[8:9]
	s_cmpk_eq_i32 s1, 0xa0
	s_cselect_b64 s[14:15], -1, 0
	s_and_b64 s[16:17], s[14:15], exec
	s_cselect_b32 s74, 8, s7
	s_or_b64 s[8:9], s[14:15], s[8:9]
	s_and_b64 s[8:9], s[8:9], exec
	s_cselect_b32 s96, s0, 0
	s_and_b32 s7, s6, 0xffffffc0
	s_mov_b32 s10, 0
	s_cmpk_lg_i32 s7, 0xc0
	s_mov_b32 s11, 1
	s_cbranch_scc1 .LBB0_839
	s_add_i32 s7, s6, 0xffffff40
	s_lshr_b32 s7, s7, 5
	s_sub_i32 s10, 1, s7
	s_mov_b32 s74, 15
	s_mov_b32 s11, 2
	s_mov_b32 s96, s0
	s_cmpk_lg_i32 s1, 0x100
	s_cbranch_scc0 .LBB0_840
